# barrier: drop the per-XCD generation bump (nobody polls it any more)
# speedup vs baseline: 1.0110x; 1.0040x over previous
.LBB0_272:
	s_lshl_b32 s20, s28, 6
	s_add_i32 s2, s20, 0x500
	s_mov_b32 s3, 0
	s_lshl_b64 s[0:1], s[2:3], 2
	s_add_u32 s0, s34, s0
	s_addc_u32 s1, s35, s1
	v_mov_b32_e32 v1, 1
	v_mov_b64_e32 v[4:5], s[0:1]
	flat_atomic_add v1, v[4:5], v1 sc0
	buffer_inv sc1
	v_cvt_f32_u32_e32 v3, v2
	v_sub_u32_e32 v4, 0, v2
	v_rcp_iflag_f32_e32 v3, v3
	s_nop 0
	v_mul_f32_e32 v3, 0x4f7ffffe, v3
	v_cvt_u32_f32_e32 v3, v3
	v_mul_lo_u32 v4, v4, v3
	v_mul_hi_u32 v4, v3, v4
	v_add_u32_e32 v3, v3, v4
	s_waitcnt vmcnt(0) lgkmcnt(0)
	v_mul_hi_u32 v3, v1, v3
	v_mul_lo_u32 v5, v3, v2
	v_add_u32_e32 v4, 1, v1
	v_sub_u32_e32 v1, v1, v5
	v_add_u32_e32 v6, 1, v3
	v_cmp_ge_u32_e32 vcc, v1, v2
	v_sub_u32_e32 v5, v1, v2
	s_nop 0
	v_cndmask_b32_e32 v3, v3, v6, vcc
	v_cndmask_b32_e32 v1, v1, v5, vcc
	v_add_u32_e32 v5, 1, v3
	v_cmp_ge_u32_e32 vcc, v1, v2
	s_nop 1
	v_cndmask_b32_e32 v1, v3, v5, vcc
	v_mad_u64_u32 v[2:3], s[0:1], v2, v1, v[2:3]
	v_cmp_ne_u32_e32 vcc, v4, v2
	s_and_saveexec_b64 s[0:1], vcc
	s_xor_b64 s[0:1], exec, s[0:1]
	s_cbranch_execz .LBB0_285
	s_movk_i32 s2, 0xd40
	s_lshl_b64 s[2:3], s[2:3], 2
	s_add_u32 s4, s34, s2
	s_addc_u32 s5, s35, s3
	v_mov_b64_e32 v[2:3], s[4:5]
	flat_load_dword v0, v[2:3] sc1
	s_waitcnt vmcnt(0) lgkmcnt(0)
	v_cmp_eq_u32_e32 vcc, v0, v1
	s_and_saveexec_b64 s[2:3], vcc
	s_cbranch_execz .LBB0_284
	s_mov_b32 s21, 1
	s_mov_b64 s[6:7], 0
	s_branch .LBB0_276

.LBB0_300:
	s_or_b64 exec, exec, s[0:1]
	s_add_i32 s0, s20, 0x900
	s_mov_b32 s1, 0
	s_lshl_b64 s[0:1], s[0:1], 2
	s_add_u32 s0, s34, s0
	s_addc_u32 s1, s35, s1
	v_mov_b32_e32 v2, 1
	v_mov_b64_e32 v[0:1], s[0:1]
	s_waitcnt vmcnt(0) lgkmcnt(0)
	s_waitcnt vmcnt(0)

.LBB0_303:
	s_or_b64 exec, exec, s[0:1]
	s_add_i32 s38, s20, 0x900
	s_lshl_b64 s[0:1], s[38:39], 2
	s_add_u32 s0, s34, s0
	s_addc_u32 s1, s35, s1
	v_mov_b64_e32 v[0:1], s[0:1]
	s_waitcnt vmcnt(0) lgkmcnt(0)
	s_waitcnt vmcnt(0)

.LBB0_401:
	s_lshl_b32 s20, s28, 6
	s_add_i32 s38, s20, 0x500
	s_lshl_b64 s[0:1], s[38:39], 2
	s_add_u32 s0, s54, s0
	s_addc_u32 s1, s55, s1
	v_mov_b64_e32 v[4:5], s[0:1]
	flat_atomic_add v3, v[4:5], v249 sc0
	buffer_inv sc1
	v_cvt_f32_u32_e32 v1, v2
	v_sub_u32_e32 v4, 0, v2
	v_rcp_iflag_f32_e32 v1, v1
	s_nop 0
	v_mul_f32_e32 v1, 0x4f7ffffe, v1
	v_cvt_u32_f32_e32 v1, v1
	v_mul_lo_u32 v4, v4, v1
	v_mul_hi_u32 v4, v1, v4
	v_add_u32_e32 v1, v1, v4
	s_waitcnt vmcnt(0) lgkmcnt(0)
	v_mul_hi_u32 v1, v3, v1
	v_mul_lo_u32 v4, v1, v2
	v_sub_u32_e32 v4, v3, v4
	v_cmp_ge_u32_e32 vcc, v4, v2
	v_add_u32_e32 v5, 1, v1
	s_nop 0
	v_cndmask_b32_e32 v1, v1, v5, vcc
	v_sub_u32_e32 v5, v4, v2
	v_cndmask_b32_e32 v4, v4, v5, vcc
	v_cmp_ge_u32_e32 vcc, v4, v2
	v_add_u32_e32 v4, 1, v1
	s_nop 0
	v_cndmask_b32_e32 v1, v1, v4, vcc
	v_add_u32_e32 v4, 1, v3
	v_mad_u64_u32 v[2:3], s[0:1], v2, v1, v[2:3]
	v_cmp_ne_u32_e32 vcc, v4, v2
	s_and_saveexec_b64 s[0:1], vcc
	s_xor_b64 s[0:1], exec, s[0:1]
	s_cbranch_execz .LBB0_414
	s_movk_i32 s38, 0xd40
	s_lshl_b64 s[2:3], s[38:39], 2
	s_add_u32 s4, s54, s2
	s_addc_u32 s5, s55, s3
	v_mov_b64_e32 v[2:3], s[4:5]
	flat_load_dword v0, v[2:3] sc1
	s_waitcnt vmcnt(0) lgkmcnt(0)
	v_cmp_eq_u32_e32 vcc, v0, v1
	s_and_saveexec_b64 s[2:3], vcc
	s_cbranch_execz .LBB0_413
	s_mov_b32 s21, 1
	s_mov_b64 s[6:7], 0
	s_branch .LBB0_405

.LBB0_429:
	s_or_b64 exec, exec, s[0:1]
	s_add_i32 s38, s20, 0x900
	s_lshl_b64 s[0:1], s[38:39], 2
	s_add_u32 s0, s54, s0
	s_addc_u32 s1, s55, s1
	v_mov_b64_e32 v[0:1], s[0:1]
	s_waitcnt vmcnt(0) lgkmcnt(0)
	s_waitcnt vmcnt(0)

.LBB0_628:
	s_lshl_b32 s20, s28, 6
	s_add_i32 s38, s20, 0x500
	s_lshl_b64 s[0:1], s[38:39], 2
	s_add_u32 s0, s34, s0
	s_addc_u32 s1, s35, s1
	v_mov_b64_e32 v[4:5], s[0:1]
	flat_atomic_add v3, v[4:5], v249 sc0
	buffer_inv sc1
	v_cvt_f32_u32_e32 v1, v2
	v_sub_u32_e32 v4, 0, v2
	v_rcp_iflag_f32_e32 v1, v1
	s_nop 0
	v_mul_f32_e32 v1, 0x4f7ffffe, v1
	v_cvt_u32_f32_e32 v1, v1
	v_mul_lo_u32 v4, v4, v1
	v_mul_hi_u32 v4, v1, v4
	v_add_u32_e32 v1, v1, v4
	s_waitcnt vmcnt(0) lgkmcnt(0)
	v_mul_hi_u32 v1, v3, v1
	v_mul_lo_u32 v4, v1, v2
	v_sub_u32_e32 v4, v3, v4
	v_cmp_ge_u32_e32 vcc, v4, v2
	v_add_u32_e32 v5, 1, v1
	s_nop 0
	v_cndmask_b32_e32 v1, v1, v5, vcc
	v_sub_u32_e32 v5, v4, v2
	v_cndmask_b32_e32 v4, v4, v5, vcc
	v_cmp_ge_u32_e32 vcc, v4, v2
	v_add_u32_e32 v4, 1, v1
	s_nop 0
	v_cndmask_b32_e32 v1, v1, v4, vcc
	v_add_u32_e32 v4, 1, v3
	v_mad_u64_u32 v[2:3], s[0:1], v2, v1, v[2:3]
	v_cmp_ne_u32_e32 vcc, v4, v2
	s_and_saveexec_b64 s[0:1], vcc
	s_xor_b64 s[0:1], exec, s[0:1]
	s_cbranch_execz .LBB0_641
	s_movk_i32 s38, 0xd40
	s_lshl_b64 s[2:3], s[38:39], 2
	s_add_u32 s4, s34, s2
	s_addc_u32 s5, s35, s3
	v_mov_b64_e32 v[2:3], s[4:5]
	flat_load_dword v0, v[2:3] sc1
	s_waitcnt vmcnt(0) lgkmcnt(0)
	v_cmp_eq_u32_e32 vcc, v0, v1
	s_and_saveexec_b64 s[2:3], vcc
	s_cbranch_execz .LBB0_640
	s_mov_b32 s21, 1
	s_mov_b64 s[6:7], 0
	s_branch .LBB0_632

.LBB0_1713:
	s_lshl_b32 s0, s0, 6
	s_add_i32 s38, s0, 0x500
	s_lshl_b64 s[2:3], s[38:39], 2
	s_add_u32 s2, s56, s2
	s_addc_u32 s3, s57, s3
	v_mov_b64_e32 v[4:5], s[2:3]
	flat_atomic_add v3, v[4:5], v249 sc0
	buffer_inv sc1
	v_cvt_f32_u32_e32 v1, v2
	v_sub_u32_e32 v4, 0, v2
	v_rcp_iflag_f32_e32 v1, v1
	s_nop 0
	v_mul_f32_e32 v1, 0x4f7ffffe, v1
	v_cvt_u32_f32_e32 v1, v1
	v_mul_lo_u32 v4, v4, v1
	v_mul_hi_u32 v4, v1, v4
	v_add_u32_e32 v1, v1, v4
	s_waitcnt vmcnt(0) lgkmcnt(0)
	v_mul_hi_u32 v1, v3, v1
	v_mul_lo_u32 v4, v1, v2
	v_sub_u32_e32 v4, v3, v4
	v_cmp_ge_u32_e32 vcc, v4, v2
	v_add_u32_e32 v5, 1, v1
	s_nop 0
	v_cndmask_b32_e32 v1, v1, v5, vcc
	v_sub_u32_e32 v5, v4, v2
	v_cndmask_b32_e32 v4, v4, v5, vcc
	v_cmp_ge_u32_e32 vcc, v4, v2
	v_add_u32_e32 v4, 1, v1
	s_nop 0
	v_cndmask_b32_e32 v1, v1, v4, vcc
	v_add_u32_e32 v4, 1, v3
	v_mad_u64_u32 v[2:3], s[2:3], v2, v1, v[2:3]
	v_cmp_ne_u32_e32 vcc, v4, v2
	s_and_saveexec_b64 s[2:3], vcc
	s_xor_b64 s[2:3], exec, s[2:3]
	s_cbranch_execz .LBB0_1726
	s_movk_i32 s38, 0xd40
	s_lshl_b64 s[4:5], s[38:39], 2
	s_add_u32 s6, s56, s4
	s_addc_u32 s7, s57, s5
	v_mov_b64_e32 v[2:3], s[6:7]
	flat_load_dword v0, v[2:3] sc1
	s_waitcnt vmcnt(0) lgkmcnt(0)
	v_cmp_eq_u32_e32 vcc, v0, v1
	s_and_saveexec_b64 s[4:5], vcc
	s_cbranch_execz .LBB0_1725
	s_mov_b32 s1, 1
	s_mov_b64 s[8:9], 0
	s_branch .LBB0_1717

.LBB0_1741:
	s_or_b64 exec, exec, s[2:3]
	s_add_i32 s38, s0, 0x900
	s_lshl_b64 s[0:1], s[38:39], 2
	s_add_u32 s0, s56, s0
	s_addc_u32 s1, s57, s1
	v_mov_b64_e32 v[0:1], s[0:1]
	s_waitcnt vmcnt(0) lgkmcnt(0)
	s_waitcnt vmcnt(0)

.LBB0_1851:
	s_lshl_b32 s0, s0, 6
	s_add_i32 s38, s0, 0x500
	s_lshl_b64 s[2:3], s[38:39], 2
	s_add_u32 s2, s62, s2
	s_addc_u32 s3, s63, s3
	v_mov_b64_e32 v[4:5], s[2:3]
	flat_atomic_add v3, v[4:5], v249 sc0
	buffer_inv sc1
	v_cvt_f32_u32_e32 v1, v2
	v_sub_u32_e32 v4, 0, v2
	v_rcp_iflag_f32_e32 v1, v1
	s_nop 0
	v_mul_f32_e32 v1, 0x4f7ffffe, v1
	v_cvt_u32_f32_e32 v1, v1
	v_mul_lo_u32 v4, v4, v1
	v_mul_hi_u32 v4, v1, v4
	v_add_u32_e32 v1, v1, v4
	s_waitcnt vmcnt(0) lgkmcnt(0)
	v_mul_hi_u32 v1, v3, v1
	v_mul_lo_u32 v4, v1, v2
	v_sub_u32_e32 v4, v3, v4
	v_cmp_ge_u32_e32 vcc, v4, v2
	v_add_u32_e32 v5, 1, v1
	s_nop 0
	v_cndmask_b32_e32 v1, v1, v5, vcc
	v_sub_u32_e32 v5, v4, v2
	v_cndmask_b32_e32 v4, v4, v5, vcc
	v_cmp_ge_u32_e32 vcc, v4, v2
	v_add_u32_e32 v4, 1, v1
	s_nop 0
	v_cndmask_b32_e32 v1, v1, v4, vcc
	v_add_u32_e32 v4, 1, v3
	v_mad_u64_u32 v[2:3], s[2:3], v2, v1, v[2:3]
	v_cmp_ne_u32_e32 vcc, v4, v2
	s_and_saveexec_b64 s[2:3], vcc
	s_xor_b64 s[2:3], exec, s[2:3]
	s_cbranch_execz .LBB0_1864
	s_movk_i32 s38, 0xd40
	s_lshl_b64 s[4:5], s[38:39], 2
	s_add_u32 s6, s62, s4
	s_addc_u32 s7, s63, s5
	v_mov_b64_e32 v[2:3], s[6:7]
	flat_load_dword v0, v[2:3] sc1
	s_waitcnt vmcnt(0) lgkmcnt(0)
	v_cmp_eq_u32_e32 vcc, v0, v1
	s_and_saveexec_b64 s[4:5], vcc
	s_cbranch_execz .LBB0_1863
	s_mov_b32 s1, 1
	s_mov_b64 s[8:9], 0
	s_branch .LBB0_1855

.LBB0_1879:
	s_or_b64 exec, exec, s[2:3]
	s_add_i32 s38, s0, 0x900
	s_lshl_b64 s[0:1], s[38:39], 2
	s_add_u32 s0, s62, s0
	s_addc_u32 s1, s63, s1
	v_mov_b64_e32 v[0:1], s[0:1]
	s_waitcnt vmcnt(0) lgkmcnt(0)
	s_waitcnt vmcnt(0)

.LBB0_1968:
	s_lshl_b32 s0, s0, 6
	s_add_i32 s38, s0, 0x500
	s_lshl_b64 s[2:3], s[38:39], 2
	s_add_u32 s2, s60, s2
	s_addc_u32 s3, s61, s3
	v_mov_b64_e32 v[4:5], s[2:3]
	flat_atomic_add v3, v[4:5], v249 sc0
	buffer_inv sc1
	v_cvt_f32_u32_e32 v1, v2
	v_sub_u32_e32 v4, 0, v2
	v_rcp_iflag_f32_e32 v1, v1
	s_nop 0
	v_mul_f32_e32 v1, 0x4f7ffffe, v1
	v_cvt_u32_f32_e32 v1, v1
	v_mul_lo_u32 v4, v4, v1
	v_mul_hi_u32 v4, v1, v4
	v_add_u32_e32 v1, v1, v4
	s_waitcnt vmcnt(0) lgkmcnt(0)
	v_mul_hi_u32 v1, v3, v1
	v_mul_lo_u32 v4, v1, v2
	v_sub_u32_e32 v4, v3, v4
	v_cmp_ge_u32_e32 vcc, v4, v2
	v_add_u32_e32 v5, 1, v1
	s_nop 0
	v_cndmask_b32_e32 v1, v1, v5, vcc
	v_sub_u32_e32 v5, v4, v2
	v_cndmask_b32_e32 v4, v4, v5, vcc
	v_cmp_ge_u32_e32 vcc, v4, v2
	v_add_u32_e32 v4, 1, v1
	s_nop 0
	v_cndmask_b32_e32 v1, v1, v4, vcc
	v_add_u32_e32 v4, 1, v3
	v_mad_u64_u32 v[2:3], s[2:3], v2, v1, v[2:3]
	v_cmp_ne_u32_e32 vcc, v4, v2
	s_and_saveexec_b64 s[2:3], vcc
	s_xor_b64 s[2:3], exec, s[2:3]
	s_cbranch_execz .LBB0_1981
	s_movk_i32 s38, 0xd40
	s_lshl_b64 s[4:5], s[38:39], 2
	s_add_u32 s6, s60, s4
	s_addc_u32 s7, s61, s5
	v_mov_b64_e32 v[2:3], s[6:7]
	flat_load_dword v0, v[2:3] sc1
	s_waitcnt vmcnt(0) lgkmcnt(0)
	v_cmp_eq_u32_e32 vcc, v0, v1
	s_and_saveexec_b64 s[4:5], vcc
	s_cbranch_execz .LBB0_1980
	s_mov_b32 s1, 1
	s_mov_b64 s[8:9], 0
	s_branch .LBB0_1972

.LBB0_1996:
	s_or_b64 exec, exec, s[2:3]
	s_add_i32 s38, s0, 0x900
	s_lshl_b64 s[0:1], s[38:39], 2
	s_add_u32 s0, s60, s0
	s_addc_u32 s1, s61, s1
	v_mov_b64_e32 v[0:1], s[0:1]
	s_waitcnt vmcnt(0) lgkmcnt(0)
	s_waitcnt vmcnt(0)
	v_mov_b32_e32 v249, v5
